# speedup vs baseline: 1.0078x; 1.0078x over previous
; #define LAS __attribute__((address_space(3)))
; __device__ __forceinline__ float lane_xor(float v, int lane, int o) { return __int_as_float(__builtin_amdgcn_ds_bpermute((lane ^ o) << 2, __float_as_int(v))); }
; template <int A0, int A1, int B0, int B1, bool LOC> ...
;     if (LOC) {
; #pragma unroll
;         for (int i = A0; i < A1; ++i) s0[i] += sbp[8 * (i >> 2) + (i & 3)] + mk0[i];
; #pragma unroll
;         for (int i = B0; i < B1; ++i) s1v[i] += sbp[32 + 8 * (i >> 2) + (i & 3)] + mk1[i];
;     }
;     float mx = -1e30f;
; #pragma unroll
;     for (int i = A0; i < A1; ++i) mx = fmaxf(mx, s0[i]);
; #pragma unroll
;     for (int i = B0; i < B1; ++i) mx = fmaxf(mx, s1v[i]);
;     mx = fmaxf(mx, lane_xor(mx, lane, 32));
;     const float mn = fmaxf(m, mx);
;     if (__any(mn > m)) { const float alpha = __builtin_amdgcn_exp2f(m - mn); lsum *= alpha;
; #pragma unroll
;         for (int i = 0; i < 16; ++i) { o0[i] *= alpha; o1[i] *= alpha; } }
; __device__ __forceinline__ void attn_blk(bool ctx_too, const bf16_t* U, bf16_t* Y, const float* nb_l, LAS unsigned char* lds, int lane, int wave, int tid) {
;     ...
;                 for (int kk = 0; kk < 4; ++kk) { const int co = ((2 * kk + hh) ^ ksw) << 4;
;                     const bf16x8 k0 = *(const LAS bf16x8*)(kbuf + kro + co), k1 = *(const LAS bf16x8*)(kbuf + 4096 + kro + co);
;                     s0 = __builtin_amdgcn_mfma_f32_32x32x16_bf16(k0, qf[kk], s0, 0, 0, 0); s1v = __builtin_amdgcn_mfma_f32_32x32x16_bf16(k1, qf[kk], s1v, 0, 0, 0); }
;                 if (st < 4) att_soft_pv<0, 16, 0, 16, false>(s0, s1v, o0, o1, m, lsum, vbuf, vro, vsw, lane, sb, mk0, mk1);
;                 else { const LAS float* sbp = sb + 64 + (h * 15 + (j - r + 7)) * 31 + 4 * hh - c + 15;
;                     if (half == 0) att_soft_pv<0, 16, 0, 4, true>(s0, s1v, o0, o1, m, lsum, vbuf, vro, vsw, lane, sbp, mk0, mk1);
;                     else att_soft_pv<12, 16, 0, 16, true>(s0, s1v, o0, o1, m, lsum, vbuf, vro, vsw, lane, sbp, mk0, mk1); }
.LBB0_485:
	s_andn2_b64 vcc, exec, s[30:31]
	s_cbranch_vccnz .LBB0_501
	v_add_u32_e32 v0, v181, v188
	ds_read_b128 v[36:39], v0 offset:16384
	ds_read_b128 v[40:43], v0 offset:20480
	v_add_u32_e32 v0, v181, v189
	ds_read_b128 v[68:71], v0 offset:16384
	ds_read_b128 v[72:75], v0 offset:20480
	v_add_u32_e32 v0, v181, v190
	s_waitcnt lgkmcnt(0)
	v_mfma_f32_32x32x16_bf16 v[52:67], v[36:39], v[100:103], 0
	s_mov_b64 s[30:31], -1
	s_and_b64 vcc, exec, s[26:27]
	v_mfma_f32_32x32x16_bf16 v[36:51], v[40:43], v[100:103], 0
	v_mfma_f32_32x32x16_bf16 v[52:67], v[68:71], v[104:107], v[52:67]
	v_mfma_f32_32x32x16_bf16 v[36:51], v[72:75], v[104:107], v[36:51]
	ds_read_b128 v[68:71], v0 offset:16384
	ds_read_b128 v[72:75], v0 offset:20480
	v_add_u32_e32 v0, v181, v191
	s_waitcnt lgkmcnt(0)
	v_mfma_f32_32x32x16_bf16 v[52:67], v[68:71], v[108:111], v[52:67]
	v_mfma_f32_32x32x16_bf16 v[36:51], v[72:75], v[108:111], v[36:51]
	ds_read_b128 v[68:71], v0 offset:16384
	ds_read_b128 v[72:75], v0 offset:20480
	s_waitcnt lgkmcnt(0)
	v_mfma_f32_32x32x16_bf16 v[52:67], v[68:71], v[112:115], v[52:67]
	v_mfma_f32_32x32x16_bf16 v[36:51], v[72:75], v[112:115], v[36:51]
	s_cbranch_vccz .LBB0_496
	s_and_b64 vcc, exec, s[4:5]
	s_cbranch_vccz .LBB0_491
	ds_read2_b32 v[0:1], v139 offset0:24 offset1:25
	ds_read2_b32 v[68:69], v139 offset0:26 offset1:27
	ds_read2_b32 v[70:71], v139 offset0:32 offset1:33
	ds_read2_b32 v[72:73], v139 offset0:34 offset1:35
	s_waitcnt lgkmcnt(0)
	v_add_f32_e32 v0, v172, v0
	s_nop 0
	v_add_f32_e32 v218, v64, v0
	v_add_f32_e32 v0, v176, v68
	v_add_f32_e32 v216, v66, v0
	v_add_f32_e32 v0, v178, v69
	v_add_f32_e32 v215, v67, v0
	v_add_f32_e32 v0, v149, v70
	v_add_f32_e32 v214, v36, v0
	v_add_f32_e32 v0, v151, v71
	v_add_f32_e32 v1, v174, v1
	v_add_f32_e32 v213, v37, v0
	v_add_f32_e32 v0, v153, v72
	v_add_f32_e32 v217, v65, v1
	v_add_f32_e32 v206, v38, v0
	ds_read2_b32 v[0:1], v139 offset0:40 offset1:41
	v_add_f32_e32 v3, v155, v73
	ds_read2_b32 v[68:69], v139 offset0:42 offset1:43
	ds_read2_b32 v[70:71], v139 offset0:48 offset1:49
	ds_read2_b32 v[72:73], v139 offset0:50 offset1:51
	v_add_f32_e32 v205, v39, v3
	v_mov_b32_e32 v202, v141
	s_waitcnt lgkmcnt(0)
	v_add_f32_e32 v0, v157, v0
	v_add_f32_e32 v207, v40, v0
	v_add_f32_e32 v0, v159, v1
	v_add_f32_e32 v204, v41, v0
	v_add_f32_e32 v0, v161, v68
	v_add_f32_e32 v203, v42, v0
	v_add_f32_e32 v0, v163, v69
	ds_read2_b32 v[68:69], v139 offset0:56 offset1:57
	v_add_f32_e32 v201, v43, v0
	v_add_f32_e32 v0, v165, v70
	v_add_f32_e32 v200, v44, v0
	v_add_f32_e32 v0, v167, v71
	ds_read2_b32 v[70:71], v139 offset0:58 offset1:59
	s_waitcnt lgkmcnt(0)
	v_add_f32_e32 v68, v173, v68
	v_add_f32_e32 v199, v48, v68
	v_add_f32_e32 v68, v175, v69
	v_add_f32_e32 v198, v49, v68
	v_add_f32_e32 v68, v177, v70
	v_add_f32_e32 v197, v50, v68
	v_add_f32_e32 v68, v179, v71
	v_add_f32_e32 v196, v51, v68
	v_max3_f32 v68, v218, s41, v217
	v_max3_f32 v68, v68, v216, v215
	v_max3_f32 v68, v68, v214, v213
	v_max3_f32 v68, v68, v206, v205
	v_add_f32_e32 v1, v169, v72
	v_max3_f32 v68, v68, v207, v204
	v_add_f32_e32 v0, v45, v0
	v_add_f32_e32 v3, v46, v1
	v_add_f32_e32 v1, v171, v73
	v_max3_f32 v68, v68, v203, v201
	v_add_f32_e32 v1, v47, v1
	v_max3_f32 v68, v68, v200, v0
	v_max3_f32 v68, v68, v3, v1
	v_max3_f32 v68, v68, v199, v198
	v_max3_f32 v68, v68, v197, v196
	v_mov_b32_e32 v69, v68
	s_nop 1
	v_permlane32_swap_b32_e32 v69, v68
	s_waitcnt lgkmcnt(0)
	v_max3_f32 v195, v143, v68, v69
	v_cmp_gt_f32_e32 vcc, v195, v143
	s_cbranch_vccz .LBB0_490
	v_sub_f32_e32 v68, v143, v195
	v_exp_f32_e32 v84, v68
	s_nop 0
	v_mul_f32_e32 v202, v141, v84
	v_pk_mul_f32 v[34:35], v[34:35], v[84:85] op_sel_hi:[1,0]
	v_pk_mul_f32 v[32:33], v[32:33], v[84:85] op_sel_hi:[1,0]
	v_pk_mul_f32 v[30:31], v[30:31], v[84:85] op_sel_hi:[1,0]
	v_pk_mul_f32 v[28:29], v[28:29], v[84:85] op_sel_hi:[1,0]
	v_pk_mul_f32 v[26:27], v[26:27], v[84:85] op_sel_hi:[1,0]
	v_pk_mul_f32 v[24:25], v[24:25], v[84:85] op_sel_hi:[1,0]
	v_pk_mul_f32 v[22:23], v[22:23], v[84:85] op_sel_hi:[1,0]
	v_pk_mul_f32 v[20:21], v[20:21], v[84:85] op_sel_hi:[1,0]
	v_pk_mul_f32 v[18:19], v[18:19], v[84:85] op_sel_hi:[1,0]
	v_pk_mul_f32 v[16:17], v[16:17], v[84:85] op_sel_hi:[1,0]
	v_pk_mul_f32 v[14:15], v[14:15], v[84:85] op_sel_hi:[1,0]
	v_pk_mul_f32 v[12:13], v[12:13], v[84:85] op_sel_hi:[1,0]
	v_pk_mul_f32 v[10:11], v[10:11], v[84:85] op_sel_hi:[1,0]
	v_pk_mul_f32 v[8:9], v[8:9], v[84:85] op_sel_hi:[1,0]
	v_pk_mul_f32 v[6:7], v[6:7], v[84:85] op_sel_hi:[1,0]
	v_pk_mul_f32 v[4:5], v[4:5], v[84:85] op_sel_hi:[1,0]

; __device__ __forceinline__ float lane_xor(float v, int lane, int o) { return __int_as_float(__builtin_amdgcn_ds_bpermute((lane ^ o) << 2, __float_as_int(v))); }
; template <int A0, int A1, int B0, int B1, bool LOC> ...
;     if (LOC) {
; #pragma unroll
;         for (int i = A0; i < A1; ++i) s0[i] += sbp[8 * (i >> 2) + (i & 3)] + mk0[i];
; #pragma unroll
;         for (int i = B0; i < B1; ++i) s1v[i] += sbp[32 + 8 * (i >> 2) + (i & 3)] + mk1[i];
;     }
;     float mx = -1e30f;
; #pragma unroll
;     for (int i = A0; i < A1; ++i) mx = fmaxf(mx, s0[i]);
; #pragma unroll
;     for (int i = B0; i < B1; ++i) mx = fmaxf(mx, s1v[i]);
;     mx = fmaxf(mx, lane_xor(mx, lane, 32));
;     const float mn = fmaxf(m, mx);
;     if (__any(mn > m)) { const float alpha = __builtin_amdgcn_exp2f(m - mn); lsum *= alpha;
; #pragma unroll
;         for (int i = 0; i < 16; ++i) { o0[i] *= alpha; o1[i] *= alpha; } }
.LBB0_491:
	s_and_b64 vcc, exec, s[30:31]
	s_cbranch_vccz .LBB0_495
	ds_read2_b32 v[0:1], v139 offset1:1
	ds_read2_b32 v[68:69], v139 offset0:2 offset1:3
	ds_read2_b32 v[70:71], v139 offset0:8 offset1:9
	ds_read2_b32 v[72:73], v139 offset0:10 offset1:11
	s_waitcnt lgkmcnt(0)
	v_add_f32_e32 v0, v148, v0
	v_add_f32_e32 v1, v150, v1
	v_add_f32_e32 v199, v52, v0
	v_add_f32_e32 v0, v53, v1
	v_add_f32_e32 v1, v152, v68
	v_add_f32_e32 v68, v156, v70
	v_add_f32_e32 v196, v56, v68
	v_add_f32_e32 v68, v158, v71
	v_add_f32_e32 v197, v57, v68
	v_add_f32_e32 v68, v160, v72
	v_add_f32_e32 v3, v154, v69
	v_add_f32_e32 v198, v58, v68
	ds_read2_b32 v[68:69], v139 offset0:16 offset1:17
	v_add_f32_e32 v70, v162, v73
	v_add_f32_e32 v200, v59, v70
	ds_read2_b32 v[70:71], v139 offset0:18 offset1:19
	ds_read2_b32 v[72:73], v139 offset0:24 offset1:25
	ds_read2_b32 v[74:75], v139 offset0:26 offset1:27
	v_add_f32_e32 v1, v54, v1
	s_waitcnt lgkmcnt(0)
	v_add_f32_e32 v68, v164, v68
	v_add_f32_e32 v205, v60, v68
	v_add_f32_e32 v68, v166, v69
	v_add_f32_e32 v206, v61, v68
	v_add_f32_e32 v68, v168, v70
	v_add_f32_e32 v207, v62, v68
	v_add_f32_e32 v68, v170, v71
	v_add_f32_e32 v213, v63, v68
	v_add_f32_e32 v68, v172, v72
	v_add_f32_e32 v214, v64, v68
	v_add_f32_e32 v68, v174, v73
	v_add_f32_e32 v215, v65, v68
	v_add_f32_e32 v70, v176, v74
	ds_read2_b32 v[68:69], v139 offset0:32 offset1:33
	v_add_f32_e32 v216, v66, v70
	v_add_f32_e32 v70, v178, v75
	v_add_f32_e32 v217, v67, v70
	ds_read2_b32 v[70:71], v139 offset0:34 offset1:35
	s_waitcnt lgkmcnt(0)
	v_add_f32_e32 v68, v149, v68
	v_add_f32_e32 v204, v36, v68
	v_add_f32_e32 v68, v151, v69
	v_add_f32_e32 v203, v37, v68
	v_add_f32_e32 v68, v153, v70
	v_add_f32_e32 v202, v38, v68
	v_add_f32_e32 v68, v155, v71
	v_add_f32_e32 v3, v55, v3
	v_add_f32_e32 v201, v39, v68
	v_max3_f32 v68, v199, s41, v0
	v_max3_f32 v68, v68, v1, v3
	v_max3_f32 v68, v68, v196, v197
	v_max3_f32 v68, v68, v198, v200
	v_max3_f32 v68, v68, v205, v206
	v_max3_f32 v68, v68, v207, v213
	v_max3_f32 v68, v68, v214, v215
	v_max3_f32 v68, v68, v216, v217
	v_max3_f32 v68, v68, v204, v203
	v_max3_f32 v68, v68, v202, v201
	v_mov_b32_e32 v69, v68
	s_nop 1
	v_permlane32_swap_b32_e32 v69, v68
	v_mov_b32_e32 v218, v141
	s_waitcnt lgkmcnt(0)
	v_max3_f32 v195, v143, v68, v69
	v_cmp_gt_f32_e32 vcc, v195, v143
	s_cbranch_vccz .LBB0_494
	v_sub_f32_e32 v68, v143, v195
	v_exp_f32_e32 v84, v68
	s_nop 0
	v_mul_f32_e32 v218, v141, v84
	v_pk_mul_f32 v[34:35], v[34:35], v[84:85] op_sel_hi:[1,0]
	v_pk_mul_f32 v[32:33], v[32:33], v[84:85] op_sel_hi:[1,0]
	v_pk_mul_f32 v[30:31], v[30:31], v[84:85] op_sel_hi:[1,0]
	v_pk_mul_f32 v[28:29], v[28:29], v[84:85] op_sel_hi:[1,0]
	v_pk_mul_f32 v[26:27], v[26:27], v[84:85] op_sel_hi:[1,0]
	v_pk_mul_f32 v[24:25], v[24:25], v[84:85] op_sel_hi:[1,0]
	v_pk_mul_f32 v[22:23], v[22:23], v[84:85] op_sel_hi:[1,0]
	v_pk_mul_f32 v[20:21], v[20:21], v[84:85] op_sel_hi:[1,0]
	v_pk_mul_f32 v[18:19], v[18:19], v[84:85] op_sel_hi:[1,0]
	v_pk_mul_f32 v[16:17], v[16:17], v[84:85] op_sel_hi:[1,0]
	v_pk_mul_f32 v[14:15], v[14:15], v[84:85] op_sel_hi:[1,0]
	v_pk_mul_f32 v[12:13], v[12:13], v[84:85] op_sel_hi:[1,0]
	v_pk_mul_f32 v[10:11], v[10:11], v[84:85] op_sel_hi:[1,0]
	v_pk_mul_f32 v[8:9], v[8:9], v[84:85] op_sel_hi:[1,0]
	v_pk_mul_f32 v[6:7], v[6:7], v[84:85] op_sel_hi:[1,0]
	v_pk_mul_f32 v[4:5], v[4:5], v[84:85] op_sel_hi:[1,0]

; __device__ __forceinline__ float lane_xor(float v, int lane, int o) { return __int_as_float(__builtin_amdgcn_ds_bpermute((lane ^ o) << 2, __float_as_int(v))); }
; template <int A0, int A1, int B0, int B1, bool LOC> ...
;     ...
;     float mx = -1e30f;
; #pragma unroll
;     for (int i = A0; i < A1; ++i) mx = fmaxf(mx, s0[i]);
; #pragma unroll
;     for (int i = B0; i < B1; ++i) mx = fmaxf(mx, s1v[i]);
;     mx = fmaxf(mx, lane_xor(mx, lane, 32));
;     const float mn = fmaxf(m, mx);
;     if (__any(mn > m)) { const float alpha = __builtin_amdgcn_exp2f(m - mn); lsum *= alpha;
; #pragma unroll
;         for (int i = 0; i < 16; ++i) { o0[i] *= alpha; o1[i] *= alpha; } }
.LBB0_496:
	s_andn2_b64 vcc, exec, s[30:31]
	s_cbranch_vccnz .LBB0_500
	s_nop 7
	v_max3_f32 v0, v52, s41, v53
	v_max3_f32 v0, v0, v54, v55
	v_max3_f32 v0, v0, v56, v57
	v_max3_f32 v0, v0, v58, v59
	v_max3_f32 v0, v0, v60, v61
	v_max3_f32 v0, v0, v62, v63
	v_max3_f32 v0, v0, v64, v65
	v_max3_f32 v0, v0, v66, v67
	v_max3_f32 v0, v0, v36, v37
	v_max3_f32 v0, v0, v38, v39
	v_max3_f32 v0, v0, v40, v41
	v_max3_f32 v0, v0, v42, v43
	v_max3_f32 v0, v0, v44, v45
	v_max3_f32 v0, v0, v46, v47
	v_max3_f32 v0, v0, v48, v49
	v_max3_f32 v0, v0, v50, v51
	v_mov_b32_e32 v1, v0
	s_nop 1
	v_permlane32_swap_b32_e32 v1, v0
	s_waitcnt lgkmcnt(0)
	v_max3_f32 v195, v143, v0, v1
	v_cmp_gt_f32_e32 vcc, v195, v143
	s_cbranch_vccz .LBB0_499
	v_sub_f32_e32 v0, v143, v195
	v_exp_f32_e32 v0, v0
	s_nop 0
	v_mul_f32_e32 v141, v141, v0
	v_pk_mul_f32 v[34:35], v[34:35], v[0:1] op_sel_hi:[1,0]
	v_pk_mul_f32 v[32:33], v[32:33], v[0:1] op_sel_hi:[1,0]
	v_pk_mul_f32 v[30:31], v[30:31], v[0:1] op_sel_hi:[1,0]
	v_pk_mul_f32 v[28:29], v[28:29], v[0:1] op_sel_hi:[1,0]
	v_pk_mul_f32 v[26:27], v[26:27], v[0:1] op_sel_hi:[1,0]
	v_pk_mul_f32 v[24:25], v[24:25], v[0:1] op_sel_hi:[1,0]
	v_pk_mul_f32 v[22:23], v[22:23], v[0:1] op_sel_hi:[1,0]
	v_pk_mul_f32 v[20:21], v[20:21], v[0:1] op_sel_hi:[1,0]
	v_pk_mul_f32 v[18:19], v[18:19], v[0:1] op_sel_hi:[1,0]
	v_pk_mul_f32 v[16:17], v[16:17], v[0:1] op_sel_hi:[1,0]
	v_pk_mul_f32 v[14:15], v[14:15], v[0:1] op_sel_hi:[1,0]
	v_pk_mul_f32 v[12:13], v[12:13], v[0:1] op_sel_hi:[1,0]
	v_pk_mul_f32 v[10:11], v[10:11], v[0:1] op_sel_hi:[1,0]
	v_pk_mul_f32 v[8:9], v[8:9], v[0:1] op_sel_hi:[1,0]
	v_pk_mul_f32 v[6:7], v[6:7], v[0:1] op_sel_hi:[1,0]
	v_pk_mul_f32 v[4:5], v[4:5], v[0:1] op_sel_hi:[1,0]

; #define LAS __attribute__((address_space(3)))
; __device__ __forceinline__ float lane_xor(float v, int lane, int o) { return __int_as_float(__builtin_amdgcn_ds_bpermute((lane ^ o) << 2, __float_as_int(v))); }
; template <int A0, int A1, int B0, int B1, bool LOC> ...
;     if (LOC) {
; #pragma unroll
;         for (int i = A0; i < A1; ++i) s0[i] += sbp[8 * (i >> 2) + (i & 3)] + mk0[i];
; #pragma unroll
;         for (int i = B0; i < B1; ++i) s1v[i] += sbp[32 + 8 * (i >> 2) + (i & 3)] + mk1[i];
;     }
;     float mx = -1e30f;
; #pragma unroll
;     for (int i = A0; i < A1; ++i) mx = fmaxf(mx, s0[i]);
; #pragma unroll
;     for (int i = B0; i < B1; ++i) mx = fmaxf(mx, s1v[i]);
;     mx = fmaxf(mx, lane_xor(mx, lane, 32));
;     const float mn = fmaxf(m, mx);
;     if (__any(mn > m)) { const float alpha = __builtin_amdgcn_exp2f(m - mn); lsum *= alpha;
; #pragma unroll
;         for (int i = 0; i < 16; ++i) { o0[i] *= alpha; o1[i] *= alpha; } }
; __device__ __forceinline__ void attn_blk(bool ctx_too, const bf16_t* U, bf16_t* Y, const float* nb_l, LAS unsigned char* lds, int lane, int wave, int tid) {
;     ...
;                 for (int kk = 0; kk < 4; ++kk) { const int co = ((2 * kk + hh) ^ ksw) << 4;
;                     const bf16x8 k0 = *(const LAS bf16x8*)(kbuf + kro + co), k1 = *(const LAS bf16x8*)(kbuf + 4096 + kro + co);
;                     s0 = __builtin_amdgcn_mfma_f32_32x32x16_bf16(k0, qf[kk], s0, 0, 0, 0); s1v = __builtin_amdgcn_mfma_f32_32x32x16_bf16(k1, qf[kk], s1v, 0, 0, 0); }
;                 if (st < 4) att_soft_pv<0, 16, 0, 16, false>(s0, s1v, o0, o1, m, lsum, vbuf, vro, vsw, lane, sb, mk0, mk1);
;                 else { const LAS float* sbp = sb + 64 + (h * 15 + (j - r + 7)) * 31 + 4 * hh - c + 15;
;                     if (half == 0) att_soft_pv<0, 16, 0, 4, true>(s0, s1v, o0, o1, m, lsum, vbuf, vro, vsw, lane, sbp, mk0, mk1);
;                     else att_soft_pv<12, 16, 0, 16, true>(s0, s1v, o0, o1, m, lsum, vbuf, vro, vsw, lane, sbp, mk0, mk1); }
.LBB0_507:
	v_add_u32_e32 v0, v181, v188
	ds_read_b128 v[36:39], v0 offset:24576
	ds_read_b128 v[40:43], v0 offset:28672
	v_add_u32_e32 v0, v181, v189
	ds_read_b128 v[68:71], v0 offset:24576
	ds_read_b128 v[72:75], v0 offset:28672
	v_add_u32_e32 v0, v181, v190
	s_waitcnt lgkmcnt(0)
	v_mfma_f32_32x32x16_bf16 v[52:67], v[36:39], v[100:103], 0
	s_mov_b64 s[28:29], -1
	s_and_b64 vcc, exec, s[26:27]
	v_mfma_f32_32x32x16_bf16 v[36:51], v[40:43], v[100:103], 0
	v_mfma_f32_32x32x16_bf16 v[52:67], v[68:71], v[104:107], v[52:67]
	v_mfma_f32_32x32x16_bf16 v[36:51], v[72:75], v[104:107], v[36:51]
	ds_read_b128 v[68:71], v0 offset:24576
	ds_read_b128 v[72:75], v0 offset:28672
	v_add_u32_e32 v0, v181, v191
	s_waitcnt lgkmcnt(0)
	v_mfma_f32_32x32x16_bf16 v[52:67], v[68:71], v[108:111], v[52:67]
	v_mfma_f32_32x32x16_bf16 v[36:51], v[72:75], v[108:111], v[36:51]
	ds_read_b128 v[68:71], v0 offset:24576
	ds_read_b128 v[72:75], v0 offset:28672
	s_waitcnt lgkmcnt(0)
	v_mfma_f32_32x32x16_bf16 v[52:67], v[68:71], v[112:115], v[52:67]
	v_mfma_f32_32x32x16_bf16 v[36:51], v[72:75], v[112:115], v[36:51]
	s_cbranch_vccz .LBB0_520
	s_and_b64 vcc, exec, s[4:5]
	s_cbranch_vccz .LBB0_515
	ds_read2_b32 v[0:1], v139 offset0:55 offset1:56
	ds_read2_b32 v[68:69], v139 offset0:57 offset1:58
	ds_read2_b32 v[70:71], v139 offset0:63 offset1:64
	ds_read2_b32 v[72:73], v139 offset0:65 offset1:66
	s_waitcnt lgkmcnt(0)
	v_add_f32_e32 v0, v172, v0
	s_nop 0
	v_add_f32_e32 v218, v64, v0
	v_add_f32_e32 v0, v176, v68
	v_add_f32_e32 v216, v66, v0
	v_add_f32_e32 v0, v178, v69
	v_add_f32_e32 v215, v67, v0
	v_add_f32_e32 v0, v149, v70
	v_add_f32_e32 v214, v36, v0
	v_add_f32_e32 v0, v151, v71
	v_add_f32_e32 v1, v174, v1
	v_add_f32_e32 v213, v37, v0
	v_add_f32_e32 v0, v153, v72
	v_add_f32_e32 v217, v65, v1
	v_add_f32_e32 v206, v38, v0
	ds_read2_b32 v[0:1], v139 offset0:71 offset1:72
	v_add_f32_e32 v3, v155, v73
	ds_read2_b32 v[68:69], v139 offset0:73 offset1:74
	ds_read2_b32 v[70:71], v139 offset0:79 offset1:80
	ds_read2_b32 v[72:73], v139 offset0:81 offset1:82
	v_add_f32_e32 v205, v39, v3
	v_mov_b32_e32 v202, v141
	s_waitcnt lgkmcnt(0)
	v_add_f32_e32 v0, v157, v0
	v_add_f32_e32 v207, v40, v0
	v_add_f32_e32 v0, v159, v1
	v_add_f32_e32 v204, v41, v0
	v_add_f32_e32 v0, v161, v68
	v_add_f32_e32 v203, v42, v0
	v_add_f32_e32 v0, v163, v69
	ds_read2_b32 v[68:69], v139 offset0:87 offset1:88
	v_add_f32_e32 v201, v43, v0
	v_add_f32_e32 v0, v165, v70
	v_add_f32_e32 v200, v44, v0
	v_add_f32_e32 v0, v167, v71
	ds_read2_b32 v[70:71], v139 offset0:89 offset1:90
	s_waitcnt lgkmcnt(0)
	v_add_f32_e32 v68, v173, v68
	v_add_f32_e32 v199, v48, v68
	v_add_f32_e32 v68, v175, v69
	v_add_f32_e32 v198, v49, v68
	v_add_f32_e32 v68, v177, v70
	v_add_f32_e32 v197, v50, v68
	v_add_f32_e32 v68, v179, v71
	v_add_f32_e32 v196, v51, v68
	v_max3_f32 v68, v218, s41, v217
	v_max3_f32 v68, v68, v216, v215
	v_max3_f32 v68, v68, v214, v213
	v_max3_f32 v68, v68, v206, v205
	v_add_f32_e32 v1, v169, v72
	v_max3_f32 v68, v68, v207, v204
	v_add_f32_e32 v0, v45, v0
	v_add_f32_e32 v3, v46, v1
	v_add_f32_e32 v1, v171, v73
	v_max3_f32 v68, v68, v203, v201
	v_add_f32_e32 v1, v47, v1
	v_max3_f32 v68, v68, v200, v0
	v_max3_f32 v68, v68, v3, v1
	v_max3_f32 v68, v68, v199, v198
	v_max3_f32 v68, v68, v197, v196
	v_mov_b32_e32 v69, v68
	s_nop 1
	v_permlane32_swap_b32_e32 v69, v68
	s_waitcnt lgkmcnt(0)
	v_max3_f32 v195, v143, v68, v69
	v_cmp_gt_f32_e32 vcc, v195, v143
	s_cbranch_vccz .LBB0_511
	v_sub_f32_e32 v68, v143, v195
	v_exp_f32_e32 v84, v68
	s_nop 0
	v_mul_f32_e32 v202, v141, v84
	v_pk_mul_f32 v[34:35], v[34:35], v[84:85] op_sel_hi:[1,0]
	v_pk_mul_f32 v[32:33], v[32:33], v[84:85] op_sel_hi:[1,0]
	v_pk_mul_f32 v[30:31], v[30:31], v[84:85] op_sel_hi:[1,0]
	v_pk_mul_f32 v[28:29], v[28:29], v[84:85] op_sel_hi:[1,0]
	v_pk_mul_f32 v[26:27], v[26:27], v[84:85] op_sel_hi:[1,0]
	v_pk_mul_f32 v[24:25], v[24:25], v[84:85] op_sel_hi:[1,0]
	v_pk_mul_f32 v[22:23], v[22:23], v[84:85] op_sel_hi:[1,0]
	v_pk_mul_f32 v[20:21], v[20:21], v[84:85] op_sel_hi:[1,0]
	v_pk_mul_f32 v[18:19], v[18:19], v[84:85] op_sel_hi:[1,0]
	v_pk_mul_f32 v[16:17], v[16:17], v[84:85] op_sel_hi:[1,0]
	v_pk_mul_f32 v[14:15], v[14:15], v[84:85] op_sel_hi:[1,0]
	v_pk_mul_f32 v[12:13], v[12:13], v[84:85] op_sel_hi:[1,0]
	v_pk_mul_f32 v[10:11], v[10:11], v[84:85] op_sel_hi:[1,0]
	v_pk_mul_f32 v[8:9], v[8:9], v[84:85] op_sel_hi:[1,0]
	v_pk_mul_f32 v[6:7], v[6:7], v[84:85] op_sel_hi:[1,0]
	v_pk_mul_f32 v[4:5], v[4:5], v[84:85] op_sel_hi:[1,0]

; __device__ __forceinline__ float lane_xor(float v, int lane, int o) { return __int_as_float(__builtin_amdgcn_ds_bpermute((lane ^ o) << 2, __float_as_int(v))); }
; template <int A0, int A1, int B0, int B1, bool LOC> ...
;     if (LOC) {
; #pragma unroll
;         for (int i = A0; i < A1; ++i) s0[i] += sbp[8 * (i >> 2) + (i & 3)] + mk0[i];
; #pragma unroll
;         for (int i = B0; i < B1; ++i) s1v[i] += sbp[32 + 8 * (i >> 2) + (i & 3)] + mk1[i];
;     }
;     float mx = -1e30f;
; #pragma unroll
;     for (int i = A0; i < A1; ++i) mx = fmaxf(mx, s0[i]);
; #pragma unroll
;     for (int i = B0; i < B1; ++i) mx = fmaxf(mx, s1v[i]);
;     mx = fmaxf(mx, lane_xor(mx, lane, 32));
;     const float mn = fmaxf(m, mx);
;     if (__any(mn > m)) { const float alpha = __builtin_amdgcn_exp2f(m - mn); lsum *= alpha;
; #pragma unroll
;         for (int i = 0; i < 16; ++i) { o0[i] *= alpha; o1[i] *= alpha; } }
.LBB0_515:
	s_cbranch_execz .LBB0_519
	ds_read2_b32 v[0:1], v139 offset0:31 offset1:32
	ds_read2_b32 v[68:69], v139 offset0:33 offset1:34
	ds_read2_b32 v[70:71], v139 offset0:39 offset1:40
	ds_read2_b32 v[72:73], v139 offset0:41 offset1:42
	s_waitcnt lgkmcnt(0)
	v_add_f32_e32 v0, v148, v0
	v_add_f32_e32 v1, v150, v1
	v_add_f32_e32 v199, v52, v0
	v_add_f32_e32 v0, v53, v1
	v_add_f32_e32 v1, v152, v68
	v_add_f32_e32 v68, v156, v70
	v_add_f32_e32 v196, v56, v68
	v_add_f32_e32 v68, v158, v71
	v_add_f32_e32 v197, v57, v68
	v_add_f32_e32 v68, v160, v72
	v_add_f32_e32 v3, v154, v69
	v_add_f32_e32 v198, v58, v68
	ds_read2_b32 v[68:69], v139 offset0:47 offset1:48
	v_add_f32_e32 v70, v162, v73
	v_add_f32_e32 v200, v59, v70
	ds_read2_b32 v[70:71], v139 offset0:49 offset1:50
	ds_read2_b32 v[72:73], v139 offset0:55 offset1:56
	ds_read2_b32 v[74:75], v139 offset0:57 offset1:58
	v_add_f32_e32 v1, v54, v1
	s_waitcnt lgkmcnt(0)
	v_add_f32_e32 v68, v164, v68
	v_add_f32_e32 v205, v60, v68
	v_add_f32_e32 v68, v166, v69
	v_add_f32_e32 v206, v61, v68
	v_add_f32_e32 v68, v168, v70
	v_add_f32_e32 v207, v62, v68
	v_add_f32_e32 v68, v170, v71
	v_add_f32_e32 v213, v63, v68
	v_add_f32_e32 v68, v172, v72
	v_add_f32_e32 v214, v64, v68
	v_add_f32_e32 v68, v174, v73
	v_add_f32_e32 v215, v65, v68
	v_add_f32_e32 v70, v176, v74
	ds_read2_b32 v[68:69], v139 offset0:63 offset1:64
	v_add_f32_e32 v216, v66, v70
	v_add_f32_e32 v70, v178, v75
	v_add_f32_e32 v217, v67, v70
	ds_read2_b32 v[70:71], v139 offset0:65 offset1:66
	s_waitcnt lgkmcnt(0)
	v_add_f32_e32 v68, v149, v68
	v_add_f32_e32 v204, v36, v68
	v_add_f32_e32 v68, v151, v69
	v_add_f32_e32 v203, v37, v68
	v_add_f32_e32 v68, v153, v70
	v_add_f32_e32 v202, v38, v68
	v_add_f32_e32 v68, v155, v71
	v_add_f32_e32 v3, v55, v3
	v_add_f32_e32 v201, v39, v68
	v_max3_f32 v68, v199, s41, v0
	v_max3_f32 v68, v68, v1, v3
	v_max3_f32 v68, v68, v196, v197
	v_max3_f32 v68, v68, v198, v200
	v_max3_f32 v68, v68, v205, v206
	v_max3_f32 v68, v68, v207, v213
	v_max3_f32 v68, v68, v214, v215
	v_max3_f32 v68, v68, v216, v217
	v_max3_f32 v68, v68, v204, v203
	v_max3_f32 v68, v68, v202, v201
	v_mov_b32_e32 v69, v68
	s_nop 1
	v_permlane32_swap_b32_e32 v69, v68
	v_mov_b32_e32 v218, v141
	s_waitcnt lgkmcnt(0)
	v_max3_f32 v195, v143, v68, v69
	v_cmp_gt_f32_e32 vcc, v195, v143
	s_cbranch_vccz .LBB0_518
	v_sub_f32_e32 v68, v143, v195
	v_exp_f32_e32 v84, v68
	s_nop 0
	v_mul_f32_e32 v218, v141, v84
	v_pk_mul_f32 v[34:35], v[34:35], v[84:85] op_sel_hi:[1,0]
	v_pk_mul_f32 v[32:33], v[32:33], v[84:85] op_sel_hi:[1,0]
	v_pk_mul_f32 v[30:31], v[30:31], v[84:85] op_sel_hi:[1,0]
	v_pk_mul_f32 v[28:29], v[28:29], v[84:85] op_sel_hi:[1,0]
	v_pk_mul_f32 v[26:27], v[26:27], v[84:85] op_sel_hi:[1,0]
	v_pk_mul_f32 v[24:25], v[24:25], v[84:85] op_sel_hi:[1,0]
	v_pk_mul_f32 v[22:23], v[22:23], v[84:85] op_sel_hi:[1,0]
	v_pk_mul_f32 v[20:21], v[20:21], v[84:85] op_sel_hi:[1,0]
	v_pk_mul_f32 v[18:19], v[18:19], v[84:85] op_sel_hi:[1,0]
	v_pk_mul_f32 v[16:17], v[16:17], v[84:85] op_sel_hi:[1,0]
	v_pk_mul_f32 v[14:15], v[14:15], v[84:85] op_sel_hi:[1,0]
	v_pk_mul_f32 v[12:13], v[12:13], v[84:85] op_sel_hi:[1,0]
	v_pk_mul_f32 v[10:11], v[10:11], v[84:85] op_sel_hi:[1,0]
	v_pk_mul_f32 v[8:9], v[8:9], v[84:85] op_sel_hi:[1,0]
	v_pk_mul_f32 v[6:7], v[6:7], v[84:85] op_sel_hi:[1,0]
	v_pk_mul_f32 v[4:5], v[4:5], v[84:85] op_sel_hi:[1,0]

; __device__ __forceinline__ float lane_xor(float v, int lane, int o) { return __int_as_float(__builtin_amdgcn_ds_bpermute((lane ^ o) << 2, __float_as_int(v))); }
; template <int A0, int A1, int B0, int B1, bool LOC> ...
;     ...
;     float mx = -1e30f;
; #pragma unroll
;     for (int i = A0; i < A1; ++i) mx = fmaxf(mx, s0[i]);
; #pragma unroll
;     for (int i = B0; i < B1; ++i) mx = fmaxf(mx, s1v[i]);
;     mx = fmaxf(mx, lane_xor(mx, lane, 32));
;     const float mn = fmaxf(m, mx);
;     if (__any(mn > m)) { const float alpha = __builtin_amdgcn_exp2f(m - mn); lsum *= alpha;
; #pragma unroll
;         for (int i = 0; i < 16; ++i) { o0[i] *= alpha; o1[i] *= alpha; } }
.LBB0_520:
	s_andn2_b64 vcc, exec, s[28:29]
	s_cbranch_vccnz .LBB0_524
	s_nop 7
	v_max3_f32 v0, v52, s41, v53
	v_max3_f32 v0, v0, v54, v55
	v_max3_f32 v0, v0, v56, v57
	v_max3_f32 v0, v0, v58, v59
	v_max3_f32 v0, v0, v60, v61
	v_max3_f32 v0, v0, v62, v63
	v_max3_f32 v0, v0, v64, v65
	v_max3_f32 v0, v0, v66, v67
	v_max3_f32 v0, v0, v36, v37
	v_max3_f32 v0, v0, v38, v39
	v_max3_f32 v0, v0, v40, v41
	v_max3_f32 v0, v0, v42, v43
	v_max3_f32 v0, v0, v44, v45
	v_max3_f32 v0, v0, v46, v47
	v_max3_f32 v0, v0, v48, v49
	v_max3_f32 v0, v0, v50, v51
	v_mov_b32_e32 v1, v0
	s_nop 1
	v_permlane32_swap_b32_e32 v1, v0
	s_waitcnt lgkmcnt(0)
	v_max3_f32 v195, v143, v0, v1
	v_cmp_gt_f32_e32 vcc, v195, v143
	s_cbranch_vccz .LBB0_523
	v_sub_f32_e32 v0, v143, v195
	v_exp_f32_e32 v0, v0
	s_nop 0
	v_mul_f32_e32 v141, v141, v0
	v_pk_mul_f32 v[34:35], v[34:35], v[0:1] op_sel_hi:[1,0]
	v_pk_mul_f32 v[32:33], v[32:33], v[0:1] op_sel_hi:[1,0]
	v_pk_mul_f32 v[30:31], v[30:31], v[0:1] op_sel_hi:[1,0]
	v_pk_mul_f32 v[28:29], v[28:29], v[0:1] op_sel_hi:[1,0]
	v_pk_mul_f32 v[26:27], v[26:27], v[0:1] op_sel_hi:[1,0]
	v_pk_mul_f32 v[24:25], v[24:25], v[0:1] op_sel_hi:[1,0]
	v_pk_mul_f32 v[22:23], v[22:23], v[0:1] op_sel_hi:[1,0]
	v_pk_mul_f32 v[20:21], v[20:21], v[0:1] op_sel_hi:[1,0]
	v_pk_mul_f32 v[18:19], v[18:19], v[0:1] op_sel_hi:[1,0]
	v_pk_mul_f32 v[16:17], v[16:17], v[0:1] op_sel_hi:[1,0]
	v_pk_mul_f32 v[14:15], v[14:15], v[0:1] op_sel_hi:[1,0]
	v_pk_mul_f32 v[12:13], v[12:13], v[0:1] op_sel_hi:[1,0]
	v_pk_mul_f32 v[10:11], v[10:11], v[0:1] op_sel_hi:[1,0]
	v_pk_mul_f32 v[8:9], v[8:9], v[0:1] op_sel_hi:[1,0]
	v_pk_mul_f32 v[6:7], v[6:7], v[0:1] op_sel_hi:[1,0]
	v_pk_mul_f32 v[4:5], v[4:5], v[0:1] op_sel_hi:[1,0]
